# barrier: first poll also reads the top-level generation (removes a theoretical early-exit window)
# speedup vs baseline: 1.0050x; 1.0016x over previous
.LBB0_102:
	s_or_b64 exec, exec, s[10:11]
	v_cvt_f32_u32_e32 v4, v2
	s_waitcnt vmcnt(0)
	v_readfirstlane_b32 s2, v3
	v_sub_u32_e32 v3, 0, v2
	v_rcp_iflag_f32_e32 v4, v4
	v_add_u32_e32 v5, s2, v1
	v_mul_f32_e32 v4, 0x4f7ffffe, v4
	v_cvt_u32_f32_e32 v4, v4
	v_mul_lo_u32 v1, v3, v4
	v_mul_hi_u32 v1, v4, v1
	v_add_u32_e32 v1, v4, v1
	v_mul_hi_u32 v1, v5, v1
	v_mul_lo_u32 v3, v1, v2
	v_sub_u32_e32 v3, v5, v3
	v_add_u32_e32 v4, 1, v1
	v_cmp_ge_u32_e32 vcc, v3, v2
	s_nop 1
	v_cndmask_b32_e32 v1, v1, v4, vcc
	v_sub_u32_e32 v4, v3, v2
	v_cndmask_b32_e32 v3, v3, v4, vcc
	v_add_u32_e32 v4, 1, v1
	v_cmp_ge_u32_e32 vcc, v3, v2
	v_add_u32_e32 v3, 1, v5
	s_nop 0
	v_cndmask_b32_e32 v1, v1, v4, vcc
	v_mul_lo_u32 v4, v2, v1
	v_add_u32_e32 v2, v4, v2
	v_cmp_ne_u32_e32 vcc, v3, v2
	s_and_saveexec_b64 s[2:3], vcc
	s_xor_b64 s[8:9], exec, s[2:3]
	s_cbranch_execz .LBB0_116
	s_waitcnt lgkmcnt(0)
	v_mov_b32_e32 v0, 0x3500
	global_load_dword v0, v0, s[84:85] sc1
	s_add_u32 s14, s84, 0x3500
	s_addc_u32 s15, s85, 0
	s_waitcnt vmcnt(0)
	v_cmp_eq_u32_e32 vcc, v0, v1
	s_and_saveexec_b64 s[10:11], vcc
	s_cbranch_execz .LBB0_115
	s_add_u32 s12, s56, 0x1457a300
	s_addc_u32 s13, s57, 0
	s_mov_b32 s2, 1
	s_mov_b64 s[16:17], 0
	v_mov_b32_e32 v0, 0
	s_branch .LBB0_106
